# speedup vs baseline: 1.0072x; 1.0030x over previous
; DI void attn_prompt_unit(const Args& a, int b, int c, int g, LAS unsigned char* lds, const int tid) {
;     ...
;     float sum = 0.f;
; #pragma unroll
;     for (int kt = 0; kt < 6; ++kt) if ((kt >> 1) >= s0) {
; #pragma unroll
;         for (int i = 0; i < 16; ++i) { const float pv = exp2f((sc[kt][i] - mx) * LOG2E); sc[kt][i] = pv; sum += pv; } }
;     sum += __shfl_xor(sum, 32);
.LBB0_373:
	v_sub_f32_e32 v32, v32, v97
	v_mul_f32_e32 v99, 0x3fb8aa3b, v32
	v_sub_f32_e32 v33, v33, v97
	v_mul_f32_e32 v101, 0x3fb8aa3b, v33
	v_exp_f32_e32 v32, v99
	v_sub_f32_e32 v34, v34, v97
	v_exp_f32_e32 v33, v101
	v_add_f32_e32 v99, v32, v100
	v_sub_f32_e32 v35, v35, v97
	v_mul_f32_e32 v100, 0x3fb8aa3b, v34
	v_mul_f32_e32 v101, 0x3fb8aa3b, v35
	v_sub_f32_e32 v36, v36, v97
	v_exp_f32_e32 v34, v100
	v_sub_f32_e32 v37, v37, v97
	v_exp_f32_e32 v35, v101
	v_mul_f32_e32 v101, 0x3fb8aa3b, v37
	v_sub_f32_e32 v38, v38, v97
	v_mul_f32_e32 v100, 0x3fb8aa3b, v36
	v_sub_f32_e32 v39, v39, v97
	v_sub_f32_e32 v40, v40, v97
	v_exp_f32_e32 v36, v100
	v_sub_f32_e32 v41, v41, v97
	v_exp_f32_e32 v37, v101
	v_mul_f32_e32 v101, 0x3fb8aa3b, v39
	v_sub_f32_e32 v42, v42, v97
	v_mul_f32_e32 v100, 0x3fb8aa3b, v38
	v_sub_f32_e32 v43, v43, v97
	v_sub_f32_e32 v44, v44, v97
	v_exp_f32_e32 v38, v100
	v_sub_f32_e32 v45, v45, v97
	v_exp_f32_e32 v39, v101
	v_mul_f32_e32 v101, 0x3fb8aa3b, v41
	v_add_f32_e32 v99, v33, v99
	v_mul_f32_e32 v100, 0x3fb8aa3b, v40
	v_add_f32_e32 v99, v34, v99
	v_sub_f32_e32 v46, v46, v97
	v_exp_f32_e32 v40, v100
	v_add_f32_e32 v99, v35, v99
	v_exp_f32_e32 v41, v101
	v_mul_f32_e32 v101, 0x3fb8aa3b, v43
	v_add_f32_e32 v99, v36, v99
	v_mul_f32_e32 v100, 0x3fb8aa3b, v42
	v_add_f32_e32 v99, v37, v99
	v_sub_f32_e32 v47, v47, v97
	v_exp_f32_e32 v42, v100
	v_add_f32_e32 v99, v38, v99
	v_exp_f32_e32 v43, v101
	v_mul_f32_e32 v101, 0x3fb8aa3b, v45
	v_add_f32_e32 v99, v39, v99
	v_mul_f32_e32 v100, 0x3fb8aa3b, v44
	v_add_f32_e32 v99, v40, v99
	v_add_f32_e32 v99, v41, v99
	v_exp_f32_e32 v44, v100
	v_add_f32_e32 v99, v42, v99
	v_exp_f32_e32 v45, v101
	v_mul_f32_e32 v101, 0x3fb8aa3b, v47
	v_add_f32_e32 v99, v43, v99
	v_mul_f32_e32 v100, 0x3fb8aa3b, v46
	v_add_f32_e32 v99, v44, v99
	v_add_f32_e32 v99, v45, v99
	v_exp_f32_e32 v46, v100
	s_nop 0
	v_exp_f32_e32 v47, v101
	v_add_f32_e32 v99, v46, v99
	v_add_f32_e32 v100, v47, v99
	s_and_b64 vcc, exec, s[40:41]
	s_cbranch_vccz .LBB0_377
	s_branch .LBB0_378
.LBB0_374:
	v_sub_f32_e32 v48, v48, v97
	v_mul_f32_e32 v99, 0x3fb8aa3b, v48
	v_sub_f32_e32 v49, v49, v97
	v_sub_f32_e32 v50, v50, v97
	v_exp_f32_e32 v48, v99
	v_mul_f32_e32 v100, 0x3fb8aa3b, v50
	v_sub_f32_e32 v51, v51, v97
	v_mul_f32_e32 v99, 0x3fb8aa3b, v49
	v_sub_f32_e32 v52, v52, v97
	v_sub_f32_e32 v53, v53, v97
	v_exp_f32_e32 v49, v99
	v_sub_f32_e32 v54, v54, v97
	v_sub_f32_e32 v55, v55, v97
	v_exp_f32_e32 v50, v100
	v_sub_f32_e32 v56, v56, v97
	v_sub_f32_e32 v57, v57, v97
	v_mul_f32_e32 v100, 0x3fb8aa3b, v51
	v_sub_f32_e32 v58, v58, v97
	v_sub_f32_e32 v59, v59, v97
	v_exp_f32_e32 v51, v100
	v_sub_f32_e32 v60, v60, v97
	v_sub_f32_e32 v61, v61, v97
	v_mul_f32_e32 v100, 0x3fb8aa3b, v52
	v_sub_f32_e32 v62, v62, v97
	v_exp_f32_e32 v52, v100
	v_add_f32_e32 v99, v48, v49
	v_add_f32_e32 v99, v50, v99
	v_mul_f32_e32 v100, 0x3fb8aa3b, v53
	v_add_f32_e32 v99, v51, v99
	v_add_f32_e32 v99, v52, v99
	v_exp_f32_e32 v53, v100
	v_sub_f32_e32 v63, v63, v97
	v_mul_f32_e32 v100, 0x3fb8aa3b, v54
	v_add_f32_e32 v99, v53, v99
	s_nop 0
	v_exp_f32_e32 v54, v100
	v_mul_f32_e32 v100, 0x3fb8aa3b, v55
	v_add_f32_e32 v99, v54, v99
	s_nop 0
	v_exp_f32_e32 v55, v100
	v_mul_f32_e32 v100, 0x3fb8aa3b, v56
	v_add_f32_e32 v99, v55, v99
	s_nop 0
	v_exp_f32_e32 v56, v100
	v_mul_f32_e32 v100, 0x3fb8aa3b, v57
	v_add_f32_e32 v99, v56, v99
	s_nop 0
	v_exp_f32_e32 v57, v100
	v_mul_f32_e32 v100, 0x3fb8aa3b, v58
	v_add_f32_e32 v99, v57, v99
	s_nop 0
	v_exp_f32_e32 v58, v100
	v_mul_f32_e32 v100, 0x3fb8aa3b, v59
	v_add_f32_e32 v99, v58, v99
	s_nop 0
	v_exp_f32_e32 v59, v100
	v_mul_f32_e32 v100, 0x3fb8aa3b, v60
	v_add_f32_e32 v99, v59, v99
	s_nop 0
	v_exp_f32_e32 v60, v100
	v_mul_f32_e32 v100, 0x3fb8aa3b, v61
	v_add_f32_e32 v99, v60, v99
	s_nop 0
	v_exp_f32_e32 v61, v100
	v_mul_f32_e32 v100, 0x3fb8aa3b, v62
	v_add_f32_e32 v99, v61, v99
	s_nop 0
	v_exp_f32_e32 v62, v100
	v_mul_f32_e32 v100, 0x3fb8aa3b, v63
	v_add_f32_e32 v99, v62, v99
	s_nop 0
	v_exp_f32_e32 v63, v100
	s_nop 0
	v_add_f32_e32 v100, v63, v99
	s_and_b64 vcc, exec, s[42:43]
	s_cbranch_vccnz .LBB0_372
.LBB0_375:
	v_sub_f32_e32 v16, v16, v97
	v_mul_f32_e32 v99, 0x3fb8aa3b, v16
	v_sub_f32_e32 v17, v17, v97
	v_mul_f32_e32 v101, 0x3fb8aa3b, v17
	v_exp_f32_e32 v16, v99
	v_sub_f32_e32 v18, v18, v97
	v_exp_f32_e32 v17, v101
	v_add_f32_e32 v99, v16, v100
	v_sub_f32_e32 v19, v19, v97
	v_mul_f32_e32 v100, 0x3fb8aa3b, v18
	v_mul_f32_e32 v101, 0x3fb8aa3b, v19
	v_sub_f32_e32 v20, v20, v97
	v_exp_f32_e32 v18, v100
	v_sub_f32_e32 v21, v21, v97
	v_exp_f32_e32 v19, v101
	v_mul_f32_e32 v101, 0x3fb8aa3b, v21
	v_sub_f32_e32 v22, v22, v97
	v_mul_f32_e32 v100, 0x3fb8aa3b, v20
	v_sub_f32_e32 v23, v23, v97
	v_sub_f32_e32 v24, v24, v97
	v_exp_f32_e32 v20, v100
	v_sub_f32_e32 v25, v25, v97
	v_exp_f32_e32 v21, v101
	v_mul_f32_e32 v101, 0x3fb8aa3b, v23
	v_sub_f32_e32 v26, v26, v97
	v_mul_f32_e32 v100, 0x3fb8aa3b, v22
	v_sub_f32_e32 v27, v27, v97
	v_sub_f32_e32 v28, v28, v97
	v_exp_f32_e32 v22, v100
	v_sub_f32_e32 v29, v29, v97
	v_exp_f32_e32 v23, v101
	v_mul_f32_e32 v101, 0x3fb8aa3b, v25
	v_add_f32_e32 v99, v17, v99
	v_mul_f32_e32 v100, 0x3fb8aa3b, v24
	v_add_f32_e32 v99, v18, v99
	v_sub_f32_e32 v30, v30, v97
	v_exp_f32_e32 v24, v100
	v_add_f32_e32 v99, v19, v99
	v_exp_f32_e32 v25, v101
	v_mul_f32_e32 v101, 0x3fb8aa3b, v27
	v_add_f32_e32 v99, v20, v99
	v_mul_f32_e32 v100, 0x3fb8aa3b, v26
	v_add_f32_e32 v99, v21, v99
	v_sub_f32_e32 v31, v31, v97
	v_exp_f32_e32 v26, v100
	v_add_f32_e32 v99, v22, v99
	v_exp_f32_e32 v27, v101
	v_mul_f32_e32 v101, 0x3fb8aa3b, v29
	v_add_f32_e32 v99, v23, v99
	v_mul_f32_e32 v100, 0x3fb8aa3b, v28
	v_add_f32_e32 v99, v24, v99
	v_add_f32_e32 v99, v25, v99
	v_exp_f32_e32 v28, v100
	v_add_f32_e32 v99, v26, v99
	v_exp_f32_e32 v29, v101
	v_mul_f32_e32 v101, 0x3fb8aa3b, v31
	v_add_f32_e32 v99, v27, v99
	v_mul_f32_e32 v100, 0x3fb8aa3b, v30
	v_add_f32_e32 v99, v28, v99
	v_add_f32_e32 v99, v29, v99
	v_exp_f32_e32 v30, v100
	s_nop 0
	v_exp_f32_e32 v31, v101
	v_add_f32_e32 v99, v30, v99
	v_add_f32_e32 v100, v31, v99
	s_and_b64 vcc, exec, s[40:41]
	s_cbranch_vccz .LBB0_373

; DI void attn_prompt_unit(const Args& a, int b, int c, int g, LAS unsigned char* lds, const int tid) {
;     ...
;     float sum = 0.f;
; #pragma unroll
;     for (int kt = 0; kt < 6; ++kt) if ((kt >> 1) >= s0) {
; #pragma unroll
;         for (int i = 0; i < 16; ++i) { const float pv = exp2f((sc[kt][i] - mx) * LOG2E); sc[kt][i] = pv; sum += pv; } }
;     sum += __shfl_xor(sum, 32);
.LBB0_377:
	v_sub_f32_e32 v0, v0, v97
	v_mul_f32_e32 v99, 0x3fb8aa3b, v0
	v_sub_f32_e32 v1, v1, v97
	v_mul_f32_e32 v101, 0x3fb8aa3b, v1
	v_exp_f32_e32 v0, v99
	v_sub_f32_e32 v2, v2, v97
	v_exp_f32_e32 v1, v101
	v_add_f32_e32 v99, v0, v100
	v_sub_f32_e32 v3, v3, v97
	v_mul_f32_e32 v100, 0x3fb8aa3b, v2
	v_mul_f32_e32 v101, 0x3fb8aa3b, v3
	v_sub_f32_e32 v4, v4, v97
	v_exp_f32_e32 v2, v100
	v_sub_f32_e32 v5, v5, v97
	v_exp_f32_e32 v3, v101
	v_mul_f32_e32 v101, 0x3fb8aa3b, v5
	v_sub_f32_e32 v6, v6, v97
	v_mul_f32_e32 v100, 0x3fb8aa3b, v4
	v_sub_f32_e32 v7, v7, v97
	v_sub_f32_e32 v8, v8, v97
	v_exp_f32_e32 v4, v100
	v_sub_f32_e32 v9, v9, v97
	v_exp_f32_e32 v5, v101
	v_mul_f32_e32 v101, 0x3fb8aa3b, v7
	v_sub_f32_e32 v10, v10, v97
	v_mul_f32_e32 v100, 0x3fb8aa3b, v6
	v_sub_f32_e32 v11, v11, v97
	v_sub_f32_e32 v12, v12, v97
	v_exp_f32_e32 v6, v100
	v_sub_f32_e32 v13, v13, v97
	v_exp_f32_e32 v7, v101
	v_mul_f32_e32 v101, 0x3fb8aa3b, v9
	v_add_f32_e32 v99, v1, v99
	v_mul_f32_e32 v100, 0x3fb8aa3b, v8
	v_add_f32_e32 v99, v2, v99
	v_sub_f32_e32 v14, v14, v97
	v_exp_f32_e32 v8, v100
	v_add_f32_e32 v99, v3, v99
	v_exp_f32_e32 v9, v101
	v_mul_f32_e32 v101, 0x3fb8aa3b, v11
	v_add_f32_e32 v99, v4, v99
	v_mul_f32_e32 v100, 0x3fb8aa3b, v10
	v_add_f32_e32 v99, v5, v99
	v_sub_f32_e32 v15, v15, v97
	v_exp_f32_e32 v10, v100
	v_add_f32_e32 v99, v6, v99
	v_exp_f32_e32 v11, v101
	v_mul_f32_e32 v101, 0x3fb8aa3b, v13
	v_add_f32_e32 v99, v7, v99
	v_mul_f32_e32 v100, 0x3fb8aa3b, v12
	v_add_f32_e32 v99, v8, v99
	v_add_f32_e32 v99, v9, v99
	v_exp_f32_e32 v12, v100
	v_add_f32_e32 v99, v10, v99
	v_exp_f32_e32 v13, v101
	v_mul_f32_e32 v101, 0x3fb8aa3b, v15
	v_add_f32_e32 v99, v11, v99
	v_mul_f32_e32 v100, 0x3fb8aa3b, v14
	v_add_f32_e32 v99, v12, v99
	v_add_f32_e32 v99, v13, v99
	v_exp_f32_e32 v14, v100
	v_cmp_gt_f32_e32 vcc, s48, v101
	s_nop 0
	s_nop 0
	v_cndmask_b32_e32 v101, 0, v202, vcc
	v_fmac_f32_e32 v101, 0x3fb8aa3b, v15
	v_exp_f32_e32 v15, v101
	v_cndmask_b32_e32 v100, 0, v203, vcc
	v_add_f32_e32 v99, v14, v99
	v_ldexp_f32 v15, v15, v100
	v_add_f32_e32 v100, v15, v99

; #define LAS __attribute__((address_space(3)))
; DI unsigned pk2(float lo, float hi) { const f32x2_t v = {lo, hi}; const bf16x2_t b = __builtin_convertvector(v, bf16x2_t); return __builtin_bit_cast(unsigned, b); }
; DI void attn_prompt_unit(const Args& a, int b, int c, int g, LAS unsigned char* lds, const int tid) {
;     ...
;     const float inv = 1.0f / (sum + exp2f((sink - mx) * LOG2E));
;     f32x16 o[2];
; #pragma unroll
;     for (int i = 0; i < 16; ++i) { o[0][i] = 0.f; o[1][i] = 0.f; }
; #pragma unroll
;     for (int kt = 0; kt < 6; ++kt) if ((kt >> 1) >= s0) {
;         s16x4 vlo[2][2], vhi[2][2];
; #pragma unroll
;         for (int s = 0; s < 2; ++s)
; #pragma unroll
;             for (int dt = 0; dt < 2; ++dt) { const LAS bf16_t* vp = Vt + (dt * 32 + r) * 200 + 32 * kt + 16 * s + 4 * h; vlo[s][dt] = *(const LAS s16x4*)vp; vhi[s][dt] = *(const LAS s16x4*)(vp + 8); }
;         __builtin_amdgcn_sched_barrier(0);
; #pragma unroll
;         for (int s = 0; s < 2; ++s) {
;             u32x4 pw;
; #pragma unroll
;             for (int e = 0; e < 4; ++e) pw[e] = pk2(sc[kt][8 * s + 2 * e], sc[kt][8 * s + 2 * e + 1]);
;             const bf16x8 pf = __builtin_bit_cast(bf16x8, pw);
; #pragma unroll
;             for (int dt = 0; dt < 2; ++dt)
;                 o[dt] = __builtin_amdgcn_mfma_f32_32x32x16_bf16(__builtin_shufflevector(vlo[s][dt], vhi[s][dt], 0, 1, 2, 3, 4, 5, 6, 7), pf, o[dt], 0, 0, 0);
;         }
;         __builtin_amdgcn_sched_barrier(0);
;     }
;     bf16_t* orow = MIX + qrow * LDMIX + (g * 4 + j) * 64;
; #pragma unroll
;     for (int dt = 0; dt < 2; ++dt)
; #pragma unroll
;         for (int i4 = 0; i4 < 4; ++i4) { u32x2 w; w.x = pk2(o[dt][4 * i4] * inv, o[dt][4 * i4 + 1] * inv); w.y = pk2(o[dt][4 * i4 + 2] * inv, o[dt][4 * i4 + 3] * inv);
;             *(u32x2*)(orow + dt * 32 + 8 * i4 + 4 * h) = w; }
.LBB0_387:
	v_add_u32_e32 v0, v108, v50
	v_add_u32_e32 v8, v108, v51
	v_add_u32_e32 v52, 0x6800, v0
	v_add_u32_e32 v53, 0x6800, v8
	ds_read2_b64 v[0:3], v52 offset0:160 offset1:162
	ds_read2_b64 v[4:7], v52 offset0:164 offset1:166
	ds_read2_b64 v[8:11], v53 offset0:160 offset1:162
	ds_read2_b64 v[12:15], v53 offset0:164 offset1:166
	v_cvt_pk_bf16_f32 v48, v99, v100
	v_cvt_pk_bf16_f32 v49, v101, v102
	v_cvt_pk_bf16_f32 v50, v103, v104
	v_cvt_pk_bf16_f32 v51, v105, v107
	s_waitcnt lgkmcnt(3)
	s_nop 0
	v_mfma_f32_32x32x16_bf16 v[32:47], v[0:3], v[48:51], v[32:47]
	v_cvt_pk_bf16_f32 v0, v106, v109
	v_cvt_pk_bf16_f32 v1, v110, v111
	v_cvt_pk_bf16_f32 v2, v114, v115
	v_cvt_pk_bf16_f32 v3, v116, v121
	s_waitcnt lgkmcnt(1)
	v_mfma_f32_32x32x16_bf16 v[16:31], v[8:11], v[48:51], v[16:31]
	v_mfma_f32_32x32x16_bf16 v[32:47], v[4:7], v[0:3], v[32:47]
	s_waitcnt lgkmcnt(0)
	v_mfma_f32_32x32x16_bf16 v[16:31], v[12:15], v[0:3], v[16:31]
	ds_read2_b64 v[0:3], v52 offset0:168 offset1:170
	ds_read2_b64 v[4:7], v52 offset0:172 offset1:174
	ds_read2_b64 v[8:11], v53 offset0:168 offset1:170
	ds_read2_b64 v[12:15], v53 offset0:172 offset1:174
	v_cvt_pk_bf16_f32 v48, v120, v122
	v_cvt_pk_bf16_f32 v49, v123, v124
	v_cvt_pk_bf16_f32 v50, v125, v126
	v_cvt_pk_bf16_f32 v51, v127, v129
	s_waitcnt lgkmcnt(3)
	s_nop 0
	v_mfma_f32_32x32x16_bf16 v[32:47], v[0:3], v[48:51], v[32:47]
	v_cvt_pk_bf16_f32 v0, v128, v130
	v_cvt_pk_bf16_f32 v1, v131, v133
	v_cvt_pk_bf16_f32 v2, v134, v135
	v_cvt_pk_bf16_f32 v3, v136, v138
	s_waitcnt lgkmcnt(1)
	v_mfma_f32_32x32x16_bf16 v[16:31], v[8:11], v[48:51], v[16:31]
	v_mfma_f32_32x32x16_bf16 v[32:47], v[4:7], v[0:3], v[32:47]
	s_waitcnt lgkmcnt(0)
	v_mfma_f32_32x32x16_bf16 v[16:31], v[12:15], v[0:3], v[16:31]
	v_sub_f32_e32 v0, v96, v97
	v_mul_f32_e32 v1, 0x3fb8aa3b, v0
	s_nop 1
	v_exp_f32_e32 v0, v1
	v_add_f32_e32 v1, v137, v98
	v_add_f32_e32 v0, v0, v1
	v_div_scale_f32 v1, s[0:1], v0, v0, 1.0
	v_rcp_f32_e32 v2, v1
	v_div_scale_f32 v3, vcc, 1.0, v0, 1.0
	v_readlane_b32 s0, v254, 13
	v_fma_f32 v4, -v1, v2, 1.0
	v_fmac_f32_e32 v2, v4, v2
	v_mul_f32_e32 v4, v3, v2
	v_fma_f32 v5, -v1, v4, v3
	v_fmac_f32_e32 v4, v5, v2
	v_fma_f32 v1, -v1, v4, v3
	v_readlane_b32 s1, v254, 14
	v_div_fmas_f32 v1, v1, v2, v4
	v_div_fixup_f32 v0, v1, v0, 1.0
	v_mov_b64_e32 v[2:3], s[0:1]
	v_mad_u64_u32 v[2:3], s[0:1], v117, s27, v[2:3]
	v_mad_u32_u24 v3, v119, s27, v3
	v_lshl_add_u64 v[2:3], v[112:113], 1, v[2:3]
	v_pk_mul_f32 v[4:5], v[0:1], v[32:33] op_sel_hi:[0,1]
	v_pk_mul_f32 v[6:7], v[0:1], v[34:35] op_sel_hi:[0,1]
	v_lshl_add_u64 v[2:3], v[2:3], 0, v[160:161]
	v_cvt_pk_bf16_f32 v4, v4, v5
	v_cvt_pk_bf16_f32 v5, v6, v7
	global_store_dwordx2 v[2:3], v[4:5], off
	v_pk_mul_f32 v[4:5], v[0:1], v[36:37] op_sel_hi:[0,1]
	v_pk_mul_f32 v[6:7], v[0:1], v[38:39] op_sel_hi:[0,1]
	v_cvt_pk_bf16_f32 v4, v4, v5
	v_cvt_pk_bf16_f32 v5, v6, v7
	global_store_dwordx2 v[2:3], v[4:5], off offset:16
	v_pk_mul_f32 v[4:5], v[0:1], v[40:41] op_sel_hi:[0,1]
	v_pk_mul_f32 v[6:7], v[0:1], v[42:43] op_sel_hi:[0,1]
	v_cvt_pk_bf16_f32 v4, v4, v5
	v_cvt_pk_bf16_f32 v5, v6, v7
	global_store_dwordx2 v[2:3], v[4:5], off offset:32
	v_pk_mul_f32 v[4:5], v[0:1], v[44:45] op_sel_hi:[0,1]
	v_pk_mul_f32 v[6:7], v[0:1], v[46:47] op_sel_hi:[0,1]
	v_cvt_pk_bf16_f32 v4, v4, v5
	v_cvt_pk_bf16_f32 v5, v6, v7
	global_store_dwordx2 v[2:3], v[4:5], off offset:48
	v_pk_mul_f32 v[4:5], v[0:1], v[16:17] op_sel_hi:[0,1]
	v_pk_mul_f32 v[6:7], v[0:1], v[18:19] op_sel_hi:[0,1]
	v_cvt_pk_bf16_f32 v4, v4, v5
	v_cvt_pk_bf16_f32 v5, v6, v7
	global_store_dwordx2 v[2:3], v[4:5], off offset:64
	v_pk_mul_f32 v[4:5], v[0:1], v[20:21] op_sel_hi:[0,1]
	v_pk_mul_f32 v[6:7], v[0:1], v[22:23] op_sel_hi:[0,1]
	v_cvt_pk_bf16_f32 v4, v4, v5
	v_cvt_pk_bf16_f32 v5, v6, v7
	global_store_dwordx2 v[2:3], v[4:5], off offset:80
	v_pk_mul_f32 v[4:5], v[0:1], v[24:25] op_sel_hi:[0,1]
	v_pk_mul_f32 v[6:7], v[0:1], v[26:27] op_sel_hi:[0,1]
	v_cvt_pk_bf16_f32 v4, v4, v5
	v_cvt_pk_bf16_f32 v5, v6, v7
	global_store_dwordx2 v[2:3], v[4:5], off offset:96
	v_pk_mul_f32 v[4:5], v[0:1], v[28:29] op_sel_hi:[0,1]
	v_pk_mul_f32 v[0:1], v[0:1], v[30:31] op_sel_hi:[0,1]
	v_cvt_pk_bf16_f32 v4, v4, v5
	v_cvt_pk_bf16_f32 v5, v0, v1
	global_store_dwordx2 v[2:3], v[4:5], off offset:112
	s_barrier
	s_cbranch_execz .LBB0_165
	s_branch .LBB0_242
